# final-norm phase: the 8 residual-row loads issued before the first wait (early vmcnt(0) after two loads removed)
# speedup vs baseline: 1.0216x; 1.0030x over previous
; #define GAS __attribute__((address_space(1)))
; __device__ __forceinline__ size_t xb_off(int m, int c) { const int rr = m & 15, C = c >> 5, P = (C & ~7) | (2 * (C & 3) + ((C >> 2) & 1)); return ((size_t)(m >> 4) * 64 + P) * 512 + rr * 32 + ((((c & 31) * 2) ^ ((rr >> 3) << 5)) >> 1); }
; __device__ __forceinline__ float row_xb_plus_parts(const bf16* XB, int m, const float* part, int nsplit, f32x4 (&v)[8], int lane) {
; #pragma unroll
;     for (int j = 0; j < 8; ++j) { const v2u r = *(const GAS v2u*)(XB + xb_off(m, 4 * lane + 256 * j)); v[j] = (f32x4){bflo(r.x), bfhi(r.x), bflo(r.y), bfhi(r.y)}; }
; __device__ __forceinline__ void final_phase(Frame& F, int nsplit, const float* part) {
;     ...
;     for (int m = gw; m < M; m += NGW) { const bool smp = m >= SEQ; f32x4 v[8];
;         float s = row_xb_plus_parts(WSP(bf16, WS_H), m, part + (size_t)(smp ? m - SEQ : 0) * D, smp ? nsplit : 0, v, F.lane);
;         if (!smp) { const f32x4 a = *(const f32x4*)(ssq + (size_t)m * 8), b = *(const f32x4*)(ssq + (size_t)m * 8 + 4); s = ((a.x + a.y) + (a.z + a.w)) + ((b.x + b.y) + (b.z + b.w)); }
.LBB0_2484:
	s_cmpk_lt_i32 s2, 0x4000
	s_cselect_b64 s[0:1], -1, 0
	s_ashr_i32 s6, s2, 4
	s_ashr_i32 s7, s6, 31
	s_and_b32 s3, s2, 15
	s_lshl_b32 s4, s2, 1
	s_lshl_b64 s[6:7], s[6:7], 16
	s_add_u32 s6, s11, s6
	s_addc_u32 s7, s12, s7
	s_lshl_b32 s3, s3, 6
	s_add_u32 s6, s6, s3
	v_bitop3_b32 v2, s4, v58, 16 bitop3:0x6c
	s_addc_u32 s7, s7, 0
	v_lshlrev_b32_e32 v2, 1, v2
	v_lshl_add_u64 v[18:19], s[6:7], 0, v[2:3]
	v_lshl_add_u64 v[18:19], v[18:19], 0, v[0:1]
	v_add_co_u32_e32 v20, vcc, s14, v18
	s_cmpk_gt_i32 s2, 0x3fff
	s_nop 0
	v_addc_co_u32_e32 v21, vcc, 0, v19, vcc
	v_add_co_u32_e32 v22, vcc, s15, v18
	s_mov_b64 s[6:7], -1
	s_nop 0
	v_addc_co_u32_e32 v23, vcc, 0, v19, vcc
	v_add_co_u32_e32 v24, vcc, s16, v18
	global_load_dwordx2 v[22:23], v[22:23], off
	s_nop 0
	v_addc_co_u32_e32 v25, vcc, 0, v19, vcc
	v_add_co_u32_e32 v26, vcc, s17, v18
	global_load_dwordx2 v[24:25], v[24:25], off
	s_nop 0
	v_addc_co_u32_e32 v27, vcc, 0, v19, vcc
	v_add_co_u32_e32 v28, vcc, s18, v18
	s_nop 1
	v_addc_co_u32_e32 v29, vcc, 0, v19, vcc
	global_load_dwordx2 v[44:45], v[26:27], off
	global_load_dwordx2 v[46:47], v[28:29], off
	v_add_co_u32_e32 v26, vcc, 0xe000, v18
	s_nop 0
	s_nop 0
	v_addc_co_u32_e32 v27, vcc, 0, v19, vcc
	global_load_dwordx2 v[48:49], v[26:27], off
	v_add_co_u32_e32 v26, vcc, s13, v18
	s_nop 0
	s_nop 0
	v_addc_co_u32_e32 v27, vcc, 0, v19, vcc
	global_load_dwordx2 v[42:43], v[18:19], off
	global_load_dwordx2 v[38:39], v[20:21], off
	global_load_dwordx2 v[40:41], v[26:27], off
	s_waitcnt vmcnt(5)
	v_lshlrev_b32_e32 v34, 16, v22
	v_and_b32_e32 v35, 0xffff0000, v22
	v_lshlrev_b32_e32 v36, 16, v23
	v_and_b32_e32 v37, 0xffff0000, v23
	v_lshlrev_b32_e32 v30, 16, v24
	v_and_b32_e32 v31, 0xffff0000, v24
	v_lshlrev_b32_e32 v32, 16, v25
	v_and_b32_e32 v33, 0xffff0000, v25
	v_lshlrev_b32_e32 v26, 16, v44
	v_and_b32_e32 v27, 0xffff0000, v44
	v_lshlrev_b32_e32 v28, 16, v45
	v_and_b32_e32 v29, 0xffff0000, v45
	s_waitcnt vmcnt(4)
	v_lshlrev_b32_e32 v22, 16, v46
	v_and_b32_e32 v23, 0xffff0000, v46
	v_lshlrev_b32_e32 v24, 16, v47
	v_and_b32_e32 v25, 0xffff0000, v47
	s_waitcnt vmcnt(3)
	v_lshlrev_b32_e32 v18, 16, v48
	v_and_b32_e32 v19, 0xffff0000, v48
	v_lshlrev_b32_e32 v20, 16, v49
	v_and_b32_e32 v21, 0xffff0000, v49
	s_cbranch_scc1 .LBB0_2486
	s_mov_b64 s[6:7], 0
